# grid-barrier census (first barrier): the 16 per-XCD counter loads issued together instead of 15 serialized round trips
# speedup vs baseline: 1.0014x; 1.0014x over previous
; __device__ __forceinline__ unsigned xb_ld(unsigned* p)              { return __hip_atomic_load(p, __ATOMIC_RELAXED, __HIP_MEMORY_SCOPE_AGENT); }
; __device__ __forceinline__ void xcd_barrier_complete(unsigned* bar, unsigned x, unsigned& nloc, unsigned& nx) {
;     const unsigned G = gridDim.x * gridDim.y * gridDim.z;
;     unsigned sum, cnt, mine, sp = 0u;
;     for (;;) {
;         sum = 0u; cnt = 0u; mine = 0u;
; #pragma unroll
;         for (unsigned j = 0; j < 16; ++j) { const unsigned c = xb_ld(&bar[XB_XCNT(j)]); sum += c; cnt += (c > 0u) ? 1u : 0u; mine = (j == x) ? c : mine; }
;         if (sum == G) break;
;         __builtin_amdgcn_s_sleep(1);
;         if ((++sp & 255u) == 0u) { if (xb_ld(&bar[XB_TMO])) break; if (sp > XB_SPIN_CAP) { atomicAdd(&bar[XB_TMO], 1u); break; } }
;     }
;     nloc = mine > 0u ? mine : 1u; nx = cnt > 0u ? cnt : 1u;
; }
.LBB0_606:
	v_readlane_b32 s6, v254, 15
	v_readlane_b32 s7, v254, 16
	v_readlane_b32 s5, v255, 27
	s_mov_b64 s[8:9], -1
	s_mov_b64 s[12:13], -1
	s_waitcnt lgkmcnt(0)
	s_nop 4
	global_load_dword v0, v1, s[6:7] sc1
	global_load_dword v2, v1, s[6:7] offset:256 sc1
	global_load_dword v3, v1, s[6:7] offset:512 sc1
	global_load_dword v4, v1, s[6:7] offset:768 sc1
	global_load_dword v5, v1, s[6:7] offset:1024 sc1
	global_load_dword v6, v1, s[6:7] offset:1280 sc1
	global_load_dword v7, v1, s[6:7] offset:1536 sc1
	global_load_dword v8, v1, s[6:7] offset:1792 sc1
	global_load_dword v9, v1, s[6:7] offset:2048 sc1
	global_load_dword v10, v1, s[6:7] offset:2304 sc1
	global_load_dword v11, v1, s[6:7] offset:2560 sc1
	global_load_dword v12, v1, s[6:7] offset:2816 sc1
	global_load_dword v13, v1, s[6:7] offset:3072 sc1
	global_load_dword v14, v1, s[6:7] offset:3328 sc1
	global_load_dword v15, v1, s[6:7] offset:3584 sc1
	global_load_dword v16, v1, s[6:7] offset:3840 sc1
	s_waitcnt vmcnt(0)
	v_add_u32_e32 v17, v2, v0
	v_add_u32_e32 v17, v17, v3
	v_add_u32_e32 v17, v17, v4
	v_add_u32_e32 v17, v17, v5
	v_add_u32_e32 v17, v17, v6
	v_add_u32_e32 v17, v17, v7
	v_add_u32_e32 v17, v17, v8
	v_add_u32_e32 v17, v17, v9
	v_add_u32_e32 v17, v17, v10
	v_add_u32_e32 v17, v17, v11
	v_add_u32_e32 v17, v17, v12
	v_add_u32_e32 v17, v17, v13
	v_add_u32_e32 v17, v17, v14
	v_add_u32_e32 v17, v17, v15
	v_add_u32_e32 v17, v17, v16
	v_cmp_eq_u32_e32 vcc, s5, v17
	s_cbranch_vccnz .LBB0_605
	s_and_b32 s5, s4, 0xff
	s_cmp_eq_u32 s5, 0
	s_mov_b64 s[14:15], -1
	s_sleep 1
	s_cbranch_scc0 .LBB0_610
	v_readlane_b32 s6, v254, 13
	v_readlane_b32 s7, v254, 14
	s_nop 4
	global_load_dword v17, v1, s[6:7] sc1
	s_waitcnt vmcnt(0)
	v_cmp_eq_u32_e32 vcc, 0, v17
	s_cbranch_vccnz .LBB0_612
	s_mov_b64 s[14:15], 0
